# mLSTM chunk: the four ssq partial reads after barrier B2 issued together, and the last K pair of the n-partial issued with the previous pair (two fewer serialized LDS round trips per chunk)
# speedup vs baseline: 1.0020x; 1.0020x over previous
; #define LAS __attribute__((address_space(3)))
; #define MFMA32(a, b, c) __builtin_amdgcn_mfma_f32_32x32x16_bf16((a), (b), (c), 0, 0, 0)
; DI float lo_f(unsigned u) { return __uint_as_float(u << 16); }
; DI float hi_f(unsigned u) { return __uint_as_float(u & 0xffff0000u); }
; DI float bf2f(unsigned short b) { return __uint_as_float((unsigned)b << 16); }
; DI void mlstm_seq(LAS unsigned char* lds, const bf16* P, const float* IFg, bf16* Hout, const float* conv_w, const float* conv_b, const float* mlg, int seq) {
;     ...
;         for (int k4 = 0; k4 < 4; ++k4) { const f32x4 wa = *(const LAS f32x4*)(gate + 256 + 16 * k4 + 4 * hh), wb = *(const LAS f32x4*)(gate + 256 + 16 * k4 + 8 + 4 * hh);
;             LAS unsigned char* p = Kt2 + (16 * k4 + 4 * hh + q4) * 192 + 2 * (32 * th + 16 * gg + 4 * p4); const v4u kq = __builtin_bit_cast(v4u, tr8(p, p + 8 * 192));
;             const bf16x8 kf2 = pack8(lo_f(kq.x) * wa[0], hi_f(kq.x) * wa[1], lo_f(kq.y) * wa[2], hi_f(kq.y) * wa[3], lo_f(kq.z) * wb[0], hi_f(kq.z) * wb[1], lo_f(kq.w) * wb[2], hi_f(kq.w) * wb[3]);
;             Cst = MFMA32(vf[k4], kf2, Cst); }
;         { float np = 0.f;
; #pragma unroll
;             for (int i = 0; i < 8; ++i) { const int s = 8 * wv + i; np += gate[256 + s] * bf2f(*(const LAS unsigned short*)(Kt + s * 144 + 2 * lane)); }
;             npart[wv * 64 + lane] = np; }
;         __syncthreads();
;         const float tot = ssq[t] + ssq[64 + t] + ssq[128 + t] + ssq[192 + t]; const float rstd = rsqrtf(tot * (1.0f / 128.0f) + 1e-6f);
.LBB0_383:
	s_or_b64 exec, exec, s[20:21]
	s_waitcnt lgkmcnt(0)
	ds_read_b128 v[2:5], v215
	ds_read_b128 v[6:9], v216
	ds_read_b64_tr_b16 v[10:11], v227 offset:18432
	ds_read_b64_tr_b16 v[12:13], v227 offset:19968
	v_pk_mul_f32 v[30:31], v[30:31], v[144:145] op_sel_hi:[1,0]
	v_pk_mul_f32 v[28:29], v[28:29], v[144:145] op_sel_hi:[1,0]
	v_pk_mul_f32 v[26:27], v[26:27], v[144:145] op_sel_hi:[1,0]
	s_waitcnt lgkmcnt(1)
	v_lshlrev_b32_e32 v32, 16, v10
	v_and_b32_e32 v10, 0xffff0000, v10
	v_mul_f32_e32 v3, v3, v10
	v_lshlrev_b32_e32 v10, 16, v11
	v_mul_f32_e32 v4, v4, v10
	v_and_b32_e32 v10, 0xffff0000, v11
	v_mul_f32_e32 v5, v5, v10
	s_waitcnt lgkmcnt(0)
	v_lshlrev_b32_e32 v10, 16, v12
	v_mul_f32_e32 v6, v6, v10
	v_and_b32_e32 v10, 0xffff0000, v12
	v_mul_f32_e32 v7, v7, v10
	v_lshlrev_b32_e32 v10, 16, v13
	v_mul_f32_e32 v8, v8, v10
	v_and_b32_e32 v10, 0xffff0000, v13
	v_mul_f32_e32 v2, v2, v32
	v_mul_f32_e32 v9, v9, v10
	v_cvt_pk_bf16_f32 v2, v2, v3
	v_cvt_pk_bf16_f32 v3, v4, v5
	v_cvt_pk_bf16_f32 v4, v6, v7
	v_cvt_pk_bf16_f32 v5, v8, v9
	ds_read_b128 v[6:9], v217
	ds_read_b128 v[10:13], v218
	ds_read_b64_tr_b16 v[32:33], v227 offset:21504
	ds_read_b64_tr_b16 v[34:35], v227 offset:23040
	v_pk_mul_f32 v[24:25], v[24:25], v[144:145] op_sel_hi:[1,0]
	v_pk_mul_f32 v[22:23], v[22:23], v[144:145] op_sel_hi:[1,0]
	v_pk_mul_f32 v[20:21], v[20:21], v[144:145] op_sel_hi:[1,0]
	s_waitcnt lgkmcnt(1)
	v_lshlrev_b32_e32 v44, 16, v32
	v_and_b32_e32 v32, 0xffff0000, v32
	v_mul_f32_e32 v7, v7, v32
	v_lshlrev_b32_e32 v32, 16, v33
	v_mul_f32_e32 v8, v8, v32
	v_and_b32_e32 v32, 0xffff0000, v33
	v_mul_f32_e32 v9, v9, v32
	s_waitcnt lgkmcnt(0)
	v_lshlrev_b32_e32 v32, 16, v34
	v_mul_f32_e32 v10, v10, v32
	v_and_b32_e32 v32, 0xffff0000, v34
	v_mul_f32_e32 v11, v11, v32
	v_lshlrev_b32_e32 v32, 16, v35
	v_mul_f32_e32 v12, v12, v32
	v_and_b32_e32 v32, 0xffff0000, v35
	v_mul_f32_e32 v6, v6, v44
	v_mul_f32_e32 v13, v13, v32
	v_cvt_pk_bf16_f32 v6, v6, v7
	v_cvt_pk_bf16_f32 v7, v8, v9
	v_cvt_pk_bf16_f32 v8, v10, v11
	v_cvt_pk_bf16_f32 v9, v12, v13
	ds_read_b128 v[10:13], v219
	ds_read_b128 v[32:35], v220
	ds_read_b64_tr_b16 v[44:45], v228 offset:18432
	ds_read_b64_tr_b16 v[46:47], v228 offset:19968
	v_pk_mul_f32 v[18:19], v[18:19], v[144:145] op_sel_hi:[1,0]
	v_pk_mul_f32 v[16:17], v[16:17], v[144:145] op_sel_hi:[1,0]
	s_mov_b32 s20, 0x800000
	s_waitcnt lgkmcnt(1)
	v_lshlrev_b32_e32 v53, 16, v44
	v_and_b32_e32 v44, 0xffff0000, v44
	v_mul_f32_e32 v11, v11, v44
	v_lshlrev_b32_e32 v44, 16, v45
	v_mul_f32_e32 v12, v12, v44
	v_and_b32_e32 v44, 0xffff0000, v45
	v_mul_f32_e32 v13, v13, v44
	s_waitcnt lgkmcnt(0)
	v_lshlrev_b32_e32 v44, 16, v46
	v_mul_f32_e32 v32, v32, v44
	v_and_b32_e32 v44, 0xffff0000, v46
	v_mul_f32_e32 v33, v33, v44
	v_lshlrev_b32_e32 v44, 16, v47
	v_mul_f32_e32 v34, v34, v44
	v_and_b32_e32 v44, 0xffff0000, v47
	v_mul_f32_e32 v10, v10, v53
	v_mul_f32_e32 v35, v35, v44
	v_cvt_pk_bf16_f32 v10, v10, v11
	v_cvt_pk_bf16_f32 v11, v12, v13
	v_cvt_pk_bf16_f32 v12, v32, v33
	v_cvt_pk_bf16_f32 v13, v34, v35
	ds_read_b128 v[32:35], v221
	ds_read_b128 v[44:47], v222
	ds_read_b64_tr_b16 v[54:55], v227 offset:27648
	ds_read_b64_tr_b16 v[56:57], v227 offset:29184
	v_mfma_f32_32x32x16_bf16 v[16:31], v[120:123], v[2:5], v[16:31]
	s_waitcnt lgkmcnt(1)
	v_lshlrev_b32_e32 v53, 16, v54
	v_mul_f32_e32 v32, v32, v53
	v_and_b32_e32 v53, 0xffff0000, v54
	v_mul_f32_e32 v33, v33, v53
	v_lshlrev_b32_e32 v53, 16, v55
	v_mul_f32_e32 v34, v34, v53
	v_and_b32_e32 v53, 0xffff0000, v55
	v_mul_f32_e32 v35, v35, v53
	s_waitcnt lgkmcnt(0)
	v_lshlrev_b32_e32 v53, 16, v56
	v_mul_f32_e32 v44, v44, v53
	v_and_b32_e32 v53, 0xffff0000, v56
	v_mul_f32_e32 v45, v45, v53
	v_lshlrev_b32_e32 v53, 16, v57
	v_mul_f32_e32 v46, v46, v53
	v_and_b32_e32 v53, 0xffff0000, v57
	v_mul_f32_e32 v47, v47, v53
	v_cvt_pk_bf16_f32 v32, v32, v33
	v_cvt_pk_bf16_f32 v33, v34, v35
	v_cvt_pk_bf16_f32 v34, v44, v45
	v_mov_b32_e32 v44, s33
	v_cvt_pk_bf16_f32 v35, v46, v47
	v_add_u32_e32 v53, s27, v210
	ds_read_b128 v[44:47], v44 offset:1024
	ds_read_u16 v54, v53 offset:9216
	ds_read_u16 v55, v53 offset:9360
	v_add_u32_e32 v56, s88, v210
	v_mfma_f32_32x32x16_bf16 v[16:31], v[108:111], v[6:9], v[16:31]
	s_waitcnt lgkmcnt(1)
	v_lshlrev_b32_e32 v54, 16, v54
	s_waitcnt lgkmcnt(0)
	v_lshlrev_b32_e32 v55, 16, v55
	v_mul_f32_e64 v44, v44, v54
	v_mul_f32_e64 v45, v45, v55
	v_add_f32_e32 v44, 0, v44
	v_add_f32_e32 v54, v44, v45
	ds_read_u16 v44, v56 offset:9216
	ds_read_u16 v45, v53 offset:9648
	v_mfma_f32_32x32x16_bf16 v[16:31], v[116:119], v[10:13], v[16:31]
	s_waitcnt lgkmcnt(1)
	v_lshlrev_b32_e32 v44, 16, v44
	s_waitcnt lgkmcnt(0)
	v_lshlrev_b32_e32 v45, 16, v45
	v_mul_f32_e64 v44, v46, v44
	v_mul_f32_e64 v45, v47, v45
	v_add_f32_e32 v44, v54, v44
	v_add_f32_e32 v57, v44, v45
	v_mov_b32_e32 v44, s26
	ds_read_b128 v[44:47], v44 offset:1024
	ds_read_u16 v54, v56 offset:9504
	ds_read_u16 v55, v53 offset:9936
	ds_read_u16 v108, v56 offset:9792
	ds_read_u16 v109, v53 offset:10224
	v_mfma_f32_32x32x16_bf16 v[16:31], v[112:115], v[32:35], v[16:31]
	s_waitcnt lgkmcnt(3)
	v_lshlrev_b32_e32 v54, 16, v54
	s_waitcnt lgkmcnt(2)
	v_lshlrev_b32_e32 v55, 16, v55
	v_mul_f32_e64 v44, v44, v54
	v_mul_f32_e64 v45, v45, v55
	v_add_f32_e32 v44, v57, v44
	v_add_f32_e32 v54, v44, v45
	s_waitcnt lgkmcnt(1)
	v_lshlrev_b32_e32 v44, 16, v108
	s_waitcnt lgkmcnt(0)
	v_lshlrev_b32_e32 v45, 16, v109
	v_pk_mul_f32 v[44:45], v[46:47], v[44:45]
	s_nop 0
	v_add_f32_e32 v44, v54, v44
	v_add_f32_e32 v44, v44, v45
	ds_write_b32 v185, v44
	s_waitcnt lgkmcnt(0)
	s_barrier
	ds_read_b32 v2, v209
	ds_read_b32 v3, v211
	ds_read_b32 v4, v212
	ds_read_b32 v5, v213
	s_waitcnt lgkmcnt(2)
	v_add_f32_e32 v2, v2, v3
	s_waitcnt lgkmcnt(1)
	v_add_f32_e32 v2, v2, v4
	s_waitcnt lgkmcnt(0)
	v_add_f32_e32 v2, v2, v5
	v_fmamk_f32 v2, v2, 0x3c000000, v192
	v_cmp_gt_f32_e32 vcc, s20, v2
	v_mul_f32_e32 v3, 0x4b800000, v2
	v_readlane_b32 s20, v251, 8
	v_cndmask_b32_e32 v2, v2, v3, vcc
	v_rsq_f32_e32 v2, v2
	v_readlane_b32 s21, v251, 9
	v_readlane_b32 s22, v251, 10
	v_readlane_b32 s23, v251, 11
	v_mul_f32_e32 v3, 0x45800000, v2
	v_cndmask_b32_e32 v8, v2, v3, vcc
	v_lshl_add_u64 v[6:7], s[20:21], 0, v[136:137]
	s_andn2_b64 vcc, exec, s[86:87]
	v_lshrrev_b32_e32 v4, 5, v194
	v_mul_u32_u24_e32 v4, 24, v4
	v_mov_b32_e32 v5, 0
	v_lshl_add_u64 v[6:7], v[6:7], 0, v[4:5]
	s_cmp_gt_u32 s89, 29
	s_cbranch_scc1 .Lhw_0
	s_cmp_lg_u64 s[72:73], 0
	s_cbranch_scc1 .Lhw_9
	s_waitcnt vmcnt(7)
	s_branch .Lhw_done
